# xn row loop software-pipelined with scalar addressing; attention epilogue gate loads batched; wout epilogue rolling window with hoisted adaLN gate loads
# speedup vs baseline: 1.1084x; 1.0227x over previous
.LBB0_340:
	v_writelane_b32 v255, s0, 45
	s_xor_b64 s[62:63], s[0:1], -1
	s_mul_i32 s68, s4, 0x2400
	v_writelane_b32 v255, s1, 46
	s_mov_b32 s0, s4
	v_writelane_b32 v255, s0, 47
	v_mov_b32_e32 v0, v252
	v_readlane_b32 s4, v253, 29
	v_writelane_b32 v255, s1, 48
	s_lshl_b64 s[0:1], s[68:69], 2
	s_add_u32 s66, s4, s0
	v_ashrrev_i32_e32 v1, 6, v0
	v_readlane_b32 s0, v253, 33
	v_readlane_b32 s5, v253, 30
	s_addc_u32 s67, s5, s1
	v_add_u32_e32 v18, s0, v1
	s_movk_i32 s0, 0x4000
	v_cmp_gt_i32_e32 vcc, s0, v18
	s_and_saveexec_b64 s[6:7], vcc
	s_cbranch_execz .LBB0_363
	v_readfirstlane_b32 s16, v18
	v_readlane_b32 s17, v255, 44
	v_lshlrev_b32_e32 v20, 4, v241
	v_lshlrev_b32_e32 v21, 3, v241
	v_lshlrev_b32_e32 v22, 2, v248
	v_lshlrev_b32_e32 v23, 2, v247
	v_lshlrev_b32_e32 v116, 2, v246
	v_lshlrev_b32_e32 v117, 2, v245
	v_lshlrev_b32_e32 v118, 2, v244
	v_lshlrev_b32_e32 v119, 2, v243
	v_readlane_b32 s4, v255, 47
	s_nop 0
	s_lshl_b32 s4, s4, 12
	s_add_u32 s14, s48, s4
	s_addc_u32 s15, s49, 0
	s_and_b64 vcc, exec, s[62:63]
	s_cbranch_vccnz .Lxn_l1
	s_cmp_lt_u32 s16, 0x2000
	s_cselect_b32 s8, s36, s38
	s_cselect_b32 s9, s37, s39
	s_and_b32 s4, s16, 0x1fff
	s_lshl_b32 s4, s4, 12
	s_add_u32 s8, s8, s4
	s_addc_u32 s9, s9, 0
	global_load_dwordx4 v[24:27], v20, s[8:9]
	global_load_dwordx4 v[28:31], v20, s[8:9] offset:1024
	global_load_dwordx4 v[32:35], v20, s[8:9] offset:2048
	global_load_dwordx4 v[36:39], v20, s[8:9] offset:3072
.Lxn_loop_l0:
	s_cmp_lt_u32 s16, 0x2000
	s_cbranch_scc1 .Lxn_idx0_l0a
	s_sub_u32 s4, s16, 0x2000
	s_lshr_b32 s4, s4, 12
	s_add_u32 s4, s4, 1
	s_mul_i32 s4, s4, 0x3000
	s_add_u32 s10, s66, s4
	s_addc_u32 s11, s67, 0
	s_branch .Lxn_idxd_l0a
.Lxn_idx0_l0a:
	s_mov_b64 s[10:11], s[66:67]
.Lxn_idxd_l0a:
	s_add_u32 s22, s10, 0x1000
	s_addc_u32 s23, s11, 0
	global_load_dwordx4 v[56:59], v20, s[14:15]
	global_load_dwordx4 v[72:75], v20, s[22:23]
	global_load_dwordx4 v[88:91], v20, s[10:11]
	global_load_dwordx4 v[60:63], v20, s[14:15] offset:1024
	global_load_dwordx4 v[76:79], v20, s[22:23] offset:1024
	global_load_dwordx4 v[92:95], v20, s[10:11] offset:1024
	global_load_dwordx4 v[64:67], v20, s[14:15] offset:2048
	global_load_dwordx4 v[80:83], v20, s[22:23] offset:2048
	global_load_dwordx4 v[96:99], v20, s[10:11] offset:2048
	global_load_dwordx4 v[68:71], v20, s[14:15] offset:3072
	global_load_dwordx4 v[84:87], v20, s[22:23] offset:3072
	global_load_dwordx4 v[100:103], v20, s[10:11] offset:3072
	s_add_u32 s5, s16, s17
	s_cmp_lt_u32 s5, 0x4000
	s_cbranch_scc0 .Lxn_nonext_l0a
	s_mov_b32 s20, s5
	s_cmp_lt_u32 s20, 0x2000
	s_cselect_b32 s18, s36, s38
	s_cselect_b32 s19, s37, s39
	s_and_b32 s4, s20, 0x1fff
	s_lshl_b32 s4, s4, 12
	s_add_u32 s18, s18, s4
	s_addc_u32 s19, s19, 0
	global_load_dwordx4 v[40:43], v20, s[18:19]
	global_load_dwordx4 v[44:47], v20, s[18:19] offset:1024
	global_load_dwordx4 v[48:51], v20, s[18:19] offset:2048
	global_load_dwordx4 v[52:55], v20, s[18:19] offset:3072
	s_waitcnt vmcnt(16)
	s_branch .Lxn_have_l0a
.Lxn_nonext_l0a:
	s_waitcnt vmcnt(12)
.Lxn_have_l0a:
	v_mul_f32_e32 v104, v25, v25
	v_mul_f32_e32 v105, v29, v29
	v_mul_f32_e32 v106, v33, v33
	v_fmac_f32_e32 v104, v24, v24
	v_fmac_f32_e32 v105, v28, v28
	v_pk_mul_f32 v[108:109], v[36:37], v[36:37]
	v_fmac_f32_e32 v106, v32, v32
	v_fmac_f32_e32 v104, v26, v26
	v_fmac_f32_e32 v105, v30, v30
	v_pk_mul_f32 v[110:111], v[38:39], v[38:39]
	v_add_f32_e32 v107, v108, v109
	v_fmac_f32_e32 v106, v34, v34
	v_fmac_f32_e32 v104, v27, v27
	v_fmac_f32_e32 v105, v31, v31
	v_add_f32_e32 v107, v110, v107
	v_fmac_f32_e32 v106, v35, v35
	v_add_f32_e32 v104, v104, v105
	v_add_f32_e32 v107, v111, v107
	v_add_f32_e32 v104, v104, v106
	v_add_f32_e32 v104, v104, v107
	ds_bpermute_b32 v105, v22, v104
	s_waitcnt lgkmcnt(0)
	v_add_f32_e32 v104, v104, v105
	ds_bpermute_b32 v105, v23, v104
	s_waitcnt lgkmcnt(0)
	v_add_f32_e32 v104, v104, v105
	ds_bpermute_b32 v105, v116, v104
	s_waitcnt lgkmcnt(0)
	v_add_f32_e32 v104, v104, v105
	ds_bpermute_b32 v105, v117, v104
	s_waitcnt lgkmcnt(0)
	v_add_f32_e32 v104, v104, v105
	ds_bpermute_b32 v105, v118, v104
	s_waitcnt lgkmcnt(0)
	v_add_f32_e32 v104, v104, v105
	ds_bpermute_b32 v105, v119, v104
	s_waitcnt lgkmcnt(0)
	v_add_f32_e32 v104, v104, v105
	v_fmamk_f32 v104, v104, 0x3a800000, v138
	s_mov_b32 s4, 0x800000
	v_mul_f32_e32 v105, 0x4b800000, v104
	v_cmp_gt_f32_e32 vcc, s4, v104
	s_nop 1
	v_cndmask_b32_e32 v104, v104, v105, vcc
	v_rsq_f32_e32 v104, v104
	s_nop 0
	v_mul_f32_e32 v105, 0x45800000, v104
	v_cndmask_b32_e32 v112, v104, v105, vcc
	v_pk_mul_f32 v[24:25], v[24:25], v[112:113] op_sel_hi:[1,0]
	v_pk_mul_f32 v[26:27], v[26:27], v[112:113] op_sel_hi:[1,0]
	v_pk_mul_f32 v[28:29], v[28:29], v[112:113] op_sel_hi:[1,0]
	v_pk_mul_f32 v[30:31], v[30:31], v[112:113] op_sel_hi:[1,0]
	v_pk_mul_f32 v[32:33], v[32:33], v[112:113] op_sel_hi:[1,0]
	v_pk_mul_f32 v[34:35], v[34:35], v[112:113] op_sel_hi:[1,0]
	v_pk_mul_f32 v[36:37], v[36:37], v[112:113] op_sel_hi:[1,0]
	v_pk_mul_f32 v[38:39], v[38:39], v[112:113] op_sel_hi:[1,0]
	s_cmp_lt_u32 s5, 0x4000
	s_cbranch_scc0 .Lxn_w0_l0a
	s_waitcnt vmcnt(4)
	s_branch .Lxn_wd_l0a

.Lxn_wd_l0a:
	s_lshl_b32 s4, s16, 11
	s_add_u32 s12, s52, s4
	s_addc_u32 s13, s53, 0
	v_pk_mul_f32 v[24:25], v[56:57], v[24:25]
	v_pk_mul_f32 v[26:27], v[58:59], v[26:27]
	v_pk_add_f32 v[72:73], v[72:73], 1.0 op_sel_hi:[1,0]
	v_pk_add_f32 v[74:75], v[74:75], 1.0 op_sel_hi:[1,0]
	v_pk_fma_f32 v[24:25], v[72:73], v[24:25], v[88:89]
	v_pk_fma_f32 v[26:27], v[74:75], v[26:27], v[90:91]
	v_cvt_pk_bf16_f32 v114, v24, v25
	v_cvt_pk_bf16_f32 v115, v26, v27
	global_store_dwordx2 v21, v[114:115], s[12:13]
	v_pk_mul_f32 v[28:29], v[60:61], v[28:29]
	v_pk_mul_f32 v[30:31], v[62:63], v[30:31]
	v_pk_add_f32 v[76:77], v[76:77], 1.0 op_sel_hi:[1,0]
	v_pk_add_f32 v[78:79], v[78:79], 1.0 op_sel_hi:[1,0]
	v_pk_fma_f32 v[28:29], v[76:77], v[28:29], v[92:93]
	v_pk_fma_f32 v[30:31], v[78:79], v[30:31], v[94:95]
	v_cvt_pk_bf16_f32 v114, v28, v29
	v_cvt_pk_bf16_f32 v115, v30, v31
	global_store_dwordx2 v21, v[114:115], s[12:13] offset:512
	v_pk_mul_f32 v[32:33], v[64:65], v[32:33]
	v_pk_mul_f32 v[34:35], v[66:67], v[34:35]
	v_pk_add_f32 v[80:81], v[80:81], 1.0 op_sel_hi:[1,0]
	v_pk_add_f32 v[82:83], v[82:83], 1.0 op_sel_hi:[1,0]
	v_pk_fma_f32 v[32:33], v[80:81], v[32:33], v[96:97]
	v_pk_fma_f32 v[34:35], v[82:83], v[34:35], v[98:99]
	v_cvt_pk_bf16_f32 v114, v32, v33
	v_cvt_pk_bf16_f32 v115, v34, v35
	global_store_dwordx2 v21, v[114:115], s[12:13] offset:1024
	v_pk_mul_f32 v[36:37], v[68:69], v[36:37]
	v_pk_mul_f32 v[38:39], v[70:71], v[38:39]
	v_pk_add_f32 v[84:85], v[84:85], 1.0 op_sel_hi:[1,0]
	v_pk_add_f32 v[86:87], v[86:87], 1.0 op_sel_hi:[1,0]
	v_pk_fma_f32 v[36:37], v[84:85], v[36:37], v[100:101]
	v_pk_fma_f32 v[38:39], v[86:87], v[38:39], v[102:103]
	v_cvt_pk_bf16_f32 v114, v36, v37
	v_cvt_pk_bf16_f32 v115, v38, v39
	global_store_dwordx2 v21, v[114:115], s[12:13] offset:1536
	s_mov_b32 s16, s5
	s_cmp_lt_u32 s16, 0x4000
	s_cbranch_scc0 .Lxn_done
	s_cmp_lt_u32 s16, 0x2000
	s_cbranch_scc1 .Lxn_idx0_l0b
	s_sub_u32 s4, s16, 0x2000
	s_lshr_b32 s4, s4, 12
	s_add_u32 s4, s4, 1
	s_mul_i32 s4, s4, 0x3000
	s_add_u32 s10, s66, s4
	s_addc_u32 s11, s67, 0
	s_branch .Lxn_idxd_l0b

.Lxn_idxd_l0b:
	s_add_u32 s22, s10, 0x1000
	s_addc_u32 s23, s11, 0
	global_load_dwordx4 v[56:59], v20, s[14:15]
	global_load_dwordx4 v[72:75], v20, s[22:23]
	global_load_dwordx4 v[88:91], v20, s[10:11]
	global_load_dwordx4 v[60:63], v20, s[14:15] offset:1024
	global_load_dwordx4 v[76:79], v20, s[22:23] offset:1024
	global_load_dwordx4 v[92:95], v20, s[10:11] offset:1024
	global_load_dwordx4 v[64:67], v20, s[14:15] offset:2048
	global_load_dwordx4 v[80:83], v20, s[22:23] offset:2048
	global_load_dwordx4 v[96:99], v20, s[10:11] offset:2048
	global_load_dwordx4 v[68:71], v20, s[14:15] offset:3072
	global_load_dwordx4 v[84:87], v20, s[22:23] offset:3072
	global_load_dwordx4 v[100:103], v20, s[10:11] offset:3072
	s_add_u32 s5, s16, s17
	s_cmp_lt_u32 s5, 0x4000
	s_cbranch_scc0 .Lxn_nonext_l0b
	s_mov_b32 s20, s5
	s_cmp_lt_u32 s20, 0x2000
	s_cselect_b32 s18, s36, s38
	s_cselect_b32 s19, s37, s39
	s_and_b32 s4, s20, 0x1fff
	s_lshl_b32 s4, s4, 12
	s_add_u32 s18, s18, s4
	s_addc_u32 s19, s19, 0
	global_load_dwordx4 v[24:27], v20, s[18:19]
	global_load_dwordx4 v[28:31], v20, s[18:19] offset:1024
	global_load_dwordx4 v[32:35], v20, s[18:19] offset:2048
	global_load_dwordx4 v[36:39], v20, s[18:19] offset:3072
	s_waitcnt vmcnt(16)
	s_branch .Lxn_have_l0b

.Lxn_have_l0b:
	v_mul_f32_e32 v104, v41, v41
	v_mul_f32_e32 v105, v45, v45
	v_mul_f32_e32 v106, v49, v49
	v_fmac_f32_e32 v104, v40, v40
	v_fmac_f32_e32 v105, v44, v44
	v_pk_mul_f32 v[108:109], v[52:53], v[52:53]
	v_fmac_f32_e32 v106, v48, v48
	v_fmac_f32_e32 v104, v42, v42
	v_fmac_f32_e32 v105, v46, v46
	v_pk_mul_f32 v[110:111], v[54:55], v[54:55]
	v_add_f32_e32 v107, v108, v109
	v_fmac_f32_e32 v106, v50, v50
	v_fmac_f32_e32 v104, v43, v43
	v_fmac_f32_e32 v105, v47, v47
	v_add_f32_e32 v107, v110, v107
	v_fmac_f32_e32 v106, v51, v51
	v_add_f32_e32 v104, v104, v105
	v_add_f32_e32 v107, v111, v107
	v_add_f32_e32 v104, v104, v106
	v_add_f32_e32 v104, v104, v107
	ds_bpermute_b32 v105, v22, v104
	s_waitcnt lgkmcnt(0)
	v_add_f32_e32 v104, v104, v105
	ds_bpermute_b32 v105, v23, v104
	s_waitcnt lgkmcnt(0)
	v_add_f32_e32 v104, v104, v105
	ds_bpermute_b32 v105, v116, v104
	s_waitcnt lgkmcnt(0)
	v_add_f32_e32 v104, v104, v105
	ds_bpermute_b32 v105, v117, v104
	s_waitcnt lgkmcnt(0)
	v_add_f32_e32 v104, v104, v105
	ds_bpermute_b32 v105, v118, v104
	s_waitcnt lgkmcnt(0)
	v_add_f32_e32 v104, v104, v105
	ds_bpermute_b32 v105, v119, v104
	s_waitcnt lgkmcnt(0)
	v_add_f32_e32 v104, v104, v105
	v_fmamk_f32 v104, v104, 0x3a800000, v138
	s_mov_b32 s4, 0x800000
	v_mul_f32_e32 v105, 0x4b800000, v104
	v_cmp_gt_f32_e32 vcc, s4, v104
	s_nop 1
	v_cndmask_b32_e32 v104, v104, v105, vcc
	v_rsq_f32_e32 v104, v104
	s_nop 0
	v_mul_f32_e32 v105, 0x45800000, v104
	v_cndmask_b32_e32 v112, v104, v105, vcc
	v_pk_mul_f32 v[40:41], v[40:41], v[112:113] op_sel_hi:[1,0]
	v_pk_mul_f32 v[42:43], v[42:43], v[112:113] op_sel_hi:[1,0]
	v_pk_mul_f32 v[44:45], v[44:45], v[112:113] op_sel_hi:[1,0]
	v_pk_mul_f32 v[46:47], v[46:47], v[112:113] op_sel_hi:[1,0]
	v_pk_mul_f32 v[48:49], v[48:49], v[112:113] op_sel_hi:[1,0]
	v_pk_mul_f32 v[50:51], v[50:51], v[112:113] op_sel_hi:[1,0]
	v_pk_mul_f32 v[52:53], v[52:53], v[112:113] op_sel_hi:[1,0]
	v_pk_mul_f32 v[54:55], v[54:55], v[112:113] op_sel_hi:[1,0]
	s_cmp_lt_u32 s5, 0x4000
	s_cbranch_scc0 .Lxn_w0_l0b
	s_waitcnt vmcnt(4)
	s_branch .Lxn_wd_l0b

.Lxn_wd_l0b:
	s_lshl_b32 s4, s16, 11
	s_add_u32 s12, s52, s4
	s_addc_u32 s13, s53, 0
	v_pk_mul_f32 v[40:41], v[56:57], v[40:41]
	v_pk_mul_f32 v[42:43], v[58:59], v[42:43]
	v_pk_add_f32 v[72:73], v[72:73], 1.0 op_sel_hi:[1,0]
	v_pk_add_f32 v[74:75], v[74:75], 1.0 op_sel_hi:[1,0]
	v_pk_fma_f32 v[40:41], v[72:73], v[40:41], v[88:89]
	v_pk_fma_f32 v[42:43], v[74:75], v[42:43], v[90:91]
	v_cvt_pk_bf16_f32 v114, v40, v41
	v_cvt_pk_bf16_f32 v115, v42, v43
	global_store_dwordx2 v21, v[114:115], s[12:13]
	v_pk_mul_f32 v[44:45], v[60:61], v[44:45]
	v_pk_mul_f32 v[46:47], v[62:63], v[46:47]
	v_pk_add_f32 v[76:77], v[76:77], 1.0 op_sel_hi:[1,0]
	v_pk_add_f32 v[78:79], v[78:79], 1.0 op_sel_hi:[1,0]
	v_pk_fma_f32 v[44:45], v[76:77], v[44:45], v[92:93]
	v_pk_fma_f32 v[46:47], v[78:79], v[46:47], v[94:95]
	v_cvt_pk_bf16_f32 v114, v44, v45
	v_cvt_pk_bf16_f32 v115, v46, v47
	global_store_dwordx2 v21, v[114:115], s[12:13] offset:512
	v_pk_mul_f32 v[48:49], v[64:65], v[48:49]
	v_pk_mul_f32 v[50:51], v[66:67], v[50:51]
	v_pk_add_f32 v[80:81], v[80:81], 1.0 op_sel_hi:[1,0]
	v_pk_add_f32 v[82:83], v[82:83], 1.0 op_sel_hi:[1,0]
	v_pk_fma_f32 v[48:49], v[80:81], v[48:49], v[96:97]
	v_pk_fma_f32 v[50:51], v[82:83], v[50:51], v[98:99]
	v_cvt_pk_bf16_f32 v114, v48, v49
	v_cvt_pk_bf16_f32 v115, v50, v51
	global_store_dwordx2 v21, v[114:115], s[12:13] offset:1024
	v_pk_mul_f32 v[52:53], v[68:69], v[52:53]
	v_pk_mul_f32 v[54:55], v[70:71], v[54:55]
	v_pk_add_f32 v[84:85], v[84:85], 1.0 op_sel_hi:[1,0]
	v_pk_add_f32 v[86:87], v[86:87], 1.0 op_sel_hi:[1,0]
	v_pk_fma_f32 v[52:53], v[84:85], v[52:53], v[100:101]
	v_pk_fma_f32 v[54:55], v[86:87], v[54:55], v[102:103]
	v_cvt_pk_bf16_f32 v114, v52, v53
	v_cvt_pk_bf16_f32 v115, v54, v55
	global_store_dwordx2 v21, v[114:115], s[12:13] offset:1536
	s_mov_b32 s16, s5
	s_cmp_lt_u32 s16, 0x4000
	s_cbranch_scc1 .Lxn_loop_l0
	s_branch .Lxn_done
.Lxn_l1:
	s_lshl_b32 s4, s16, 11
	s_add_u32 s8, s30, s4
	s_addc_u32 s9, s31, 0
	global_load_dwordx2 v[24:25], v21, s[8:9]
	global_load_dwordx2 v[28:29], v21, s[8:9] offset:512
	global_load_dwordx2 v[32:33], v21, s[8:9] offset:1024
	global_load_dwordx2 v[36:37], v21, s[8:9] offset:1536

.Lxn_idxd_l1a:
	s_add_u32 s22, s10, 0x1000
	s_addc_u32 s23, s11, 0
	global_load_dwordx4 v[56:59], v20, s[14:15]
	global_load_dwordx4 v[72:75], v20, s[22:23]
	global_load_dwordx4 v[88:91], v20, s[10:11]
	global_load_dwordx4 v[60:63], v20, s[14:15] offset:1024
	global_load_dwordx4 v[76:79], v20, s[22:23] offset:1024
	global_load_dwordx4 v[92:95], v20, s[10:11] offset:1024
	global_load_dwordx4 v[64:67], v20, s[14:15] offset:2048
	global_load_dwordx4 v[80:83], v20, s[22:23] offset:2048
	global_load_dwordx4 v[96:99], v20, s[10:11] offset:2048
	global_load_dwordx4 v[68:71], v20, s[14:15] offset:3072
	global_load_dwordx4 v[84:87], v20, s[22:23] offset:3072
	global_load_dwordx4 v[100:103], v20, s[10:11] offset:3072
	s_add_u32 s5, s16, s17
	s_cmp_lt_u32 s5, 0x4000
	s_cbranch_scc0 .Lxn_nonext_l1a
	s_mov_b32 s20, s5
	s_lshl_b32 s4, s20, 11
	s_add_u32 s18, s30, s4
	s_addc_u32 s19, s31, 0
	global_load_dwordx2 v[40:41], v21, s[18:19]
	global_load_dwordx2 v[44:45], v21, s[18:19] offset:512
	global_load_dwordx2 v[48:49], v21, s[18:19] offset:1024
	global_load_dwordx2 v[52:53], v21, s[18:19] offset:1536
	s_waitcnt vmcnt(16)
	s_branch .Lxn_have_l1a

.Lxn_have_l1a:
	v_and_b32_e32 v39, 0xffff0000, v37
	v_lshlrev_b32_e32 v38, 16, v37
	v_and_b32_e32 v37, 0xffff0000, v36
	v_lshlrev_b32_e32 v36, 16, v36
	v_and_b32_e32 v35, 0xffff0000, v33
	v_lshlrev_b32_e32 v34, 16, v33
	v_and_b32_e32 v33, 0xffff0000, v32
	v_lshlrev_b32_e32 v32, 16, v32
	v_and_b32_e32 v31, 0xffff0000, v29
	v_lshlrev_b32_e32 v30, 16, v29
	v_and_b32_e32 v29, 0xffff0000, v28
	v_lshlrev_b32_e32 v28, 16, v28
	v_and_b32_e32 v27, 0xffff0000, v25
	v_lshlrev_b32_e32 v26, 16, v25
	v_and_b32_e32 v25, 0xffff0000, v24
	v_lshlrev_b32_e32 v24, 16, v24
	v_mul_f32_e32 v104, v25, v25
	v_mul_f32_e32 v105, v29, v29
	v_mul_f32_e32 v106, v33, v33
	v_fmac_f32_e32 v104, v24, v24
	v_fmac_f32_e32 v105, v28, v28
	v_pk_mul_f32 v[108:109], v[36:37], v[36:37]
	v_fmac_f32_e32 v106, v32, v32
	v_fmac_f32_e32 v104, v26, v26
	v_fmac_f32_e32 v105, v30, v30
	v_pk_mul_f32 v[110:111], v[38:39], v[38:39]
	v_add_f32_e32 v107, v108, v109
	v_fmac_f32_e32 v106, v34, v34
	v_fmac_f32_e32 v104, v27, v27
	v_fmac_f32_e32 v105, v31, v31
	v_add_f32_e32 v107, v110, v107
	v_fmac_f32_e32 v106, v35, v35
	v_add_f32_e32 v104, v104, v105
	v_add_f32_e32 v107, v111, v107
	v_add_f32_e32 v104, v104, v106
	v_add_f32_e32 v104, v104, v107
	ds_bpermute_b32 v105, v22, v104
	s_waitcnt lgkmcnt(0)
	v_add_f32_e32 v104, v104, v105
	ds_bpermute_b32 v105, v23, v104
	s_waitcnt lgkmcnt(0)
	v_add_f32_e32 v104, v104, v105
	ds_bpermute_b32 v105, v116, v104
	s_waitcnt lgkmcnt(0)
	v_add_f32_e32 v104, v104, v105
	ds_bpermute_b32 v105, v117, v104
	s_waitcnt lgkmcnt(0)
	v_add_f32_e32 v104, v104, v105
	ds_bpermute_b32 v105, v118, v104
	s_waitcnt lgkmcnt(0)
	v_add_f32_e32 v104, v104, v105
	ds_bpermute_b32 v105, v119, v104
	s_waitcnt lgkmcnt(0)
	v_add_f32_e32 v104, v104, v105
	v_fmamk_f32 v104, v104, 0x3a800000, v138
	s_mov_b32 s4, 0x800000
	v_mul_f32_e32 v105, 0x4b800000, v104
	v_cmp_gt_f32_e32 vcc, s4, v104
	s_nop 1
	v_cndmask_b32_e32 v104, v104, v105, vcc
	v_rsq_f32_e32 v104, v104
	s_nop 0
	v_mul_f32_e32 v105, 0x45800000, v104
	v_cndmask_b32_e32 v112, v104, v105, vcc
	v_pk_mul_f32 v[24:25], v[24:25], v[112:113] op_sel_hi:[1,0]
	v_pk_mul_f32 v[26:27], v[26:27], v[112:113] op_sel_hi:[1,0]
	v_pk_mul_f32 v[28:29], v[28:29], v[112:113] op_sel_hi:[1,0]
	v_pk_mul_f32 v[30:31], v[30:31], v[112:113] op_sel_hi:[1,0]
	v_pk_mul_f32 v[32:33], v[32:33], v[112:113] op_sel_hi:[1,0]
	v_pk_mul_f32 v[34:35], v[34:35], v[112:113] op_sel_hi:[1,0]
	v_pk_mul_f32 v[36:37], v[36:37], v[112:113] op_sel_hi:[1,0]
	v_pk_mul_f32 v[38:39], v[38:39], v[112:113] op_sel_hi:[1,0]
	s_cmp_lt_u32 s5, 0x4000
	s_cbranch_scc0 .Lxn_w0_l1a
	s_waitcnt vmcnt(4)
	s_branch .Lxn_wd_l1a

.Lxn_idxd_l1b:
	s_add_u32 s22, s10, 0x1000
	s_addc_u32 s23, s11, 0
	global_load_dwordx4 v[56:59], v20, s[14:15]
	global_load_dwordx4 v[72:75], v20, s[22:23]
	global_load_dwordx4 v[88:91], v20, s[10:11]
	global_load_dwordx4 v[60:63], v20, s[14:15] offset:1024
	global_load_dwordx4 v[76:79], v20, s[22:23] offset:1024
	global_load_dwordx4 v[92:95], v20, s[10:11] offset:1024
	global_load_dwordx4 v[64:67], v20, s[14:15] offset:2048
	global_load_dwordx4 v[80:83], v20, s[22:23] offset:2048
	global_load_dwordx4 v[96:99], v20, s[10:11] offset:2048
	global_load_dwordx4 v[68:71], v20, s[14:15] offset:3072
	global_load_dwordx4 v[84:87], v20, s[22:23] offset:3072
	global_load_dwordx4 v[100:103], v20, s[10:11] offset:3072
	s_add_u32 s5, s16, s17
	s_cmp_lt_u32 s5, 0x4000
	s_cbranch_scc0 .Lxn_nonext_l1b
	s_mov_b32 s20, s5
	s_lshl_b32 s4, s20, 11
	s_add_u32 s18, s30, s4
	s_addc_u32 s19, s31, 0
	global_load_dwordx2 v[24:25], v21, s[18:19]
	global_load_dwordx2 v[28:29], v21, s[18:19] offset:512
	global_load_dwordx2 v[32:33], v21, s[18:19] offset:1024
	global_load_dwordx2 v[36:37], v21, s[18:19] offset:1536
	s_waitcnt vmcnt(16)
	s_branch .Lxn_have_l1b

.Lxn_have_l1b:
	v_and_b32_e32 v55, 0xffff0000, v53
	v_lshlrev_b32_e32 v54, 16, v53
	v_and_b32_e32 v53, 0xffff0000, v52
	v_lshlrev_b32_e32 v52, 16, v52
	v_and_b32_e32 v51, 0xffff0000, v49
	v_lshlrev_b32_e32 v50, 16, v49
	v_and_b32_e32 v49, 0xffff0000, v48
	v_lshlrev_b32_e32 v48, 16, v48
	v_and_b32_e32 v47, 0xffff0000, v45
	v_lshlrev_b32_e32 v46, 16, v45
	v_and_b32_e32 v45, 0xffff0000, v44
	v_lshlrev_b32_e32 v44, 16, v44
	v_and_b32_e32 v43, 0xffff0000, v41
	v_lshlrev_b32_e32 v42, 16, v41
	v_and_b32_e32 v41, 0xffff0000, v40
	v_lshlrev_b32_e32 v40, 16, v40
	v_mul_f32_e32 v104, v41, v41
	v_mul_f32_e32 v105, v45, v45
	v_mul_f32_e32 v106, v49, v49
	v_fmac_f32_e32 v104, v40, v40
	v_fmac_f32_e32 v105, v44, v44
	v_pk_mul_f32 v[108:109], v[52:53], v[52:53]
	v_fmac_f32_e32 v106, v48, v48
	v_fmac_f32_e32 v104, v42, v42
	v_fmac_f32_e32 v105, v46, v46
	v_pk_mul_f32 v[110:111], v[54:55], v[54:55]
	v_add_f32_e32 v107, v108, v109
	v_fmac_f32_e32 v106, v50, v50
	v_fmac_f32_e32 v104, v43, v43
	v_fmac_f32_e32 v105, v47, v47
	v_add_f32_e32 v107, v110, v107
	v_fmac_f32_e32 v106, v51, v51
	v_add_f32_e32 v104, v104, v105
	v_add_f32_e32 v107, v111, v107
	v_add_f32_e32 v104, v104, v106
	v_add_f32_e32 v104, v104, v107
	ds_bpermute_b32 v105, v22, v104
	s_waitcnt lgkmcnt(0)
	v_add_f32_e32 v104, v104, v105
	ds_bpermute_b32 v105, v23, v104
	s_waitcnt lgkmcnt(0)
	v_add_f32_e32 v104, v104, v105
	ds_bpermute_b32 v105, v116, v104
	s_waitcnt lgkmcnt(0)
	v_add_f32_e32 v104, v104, v105
	ds_bpermute_b32 v105, v117, v104
	s_waitcnt lgkmcnt(0)
	v_add_f32_e32 v104, v104, v105
	ds_bpermute_b32 v105, v118, v104
	s_waitcnt lgkmcnt(0)
	v_add_f32_e32 v104, v104, v105
	ds_bpermute_b32 v105, v119, v104
	s_waitcnt lgkmcnt(0)
	v_add_f32_e32 v104, v104, v105
	v_fmamk_f32 v104, v104, 0x3a800000, v138
	s_mov_b32 s4, 0x800000
	v_mul_f32_e32 v105, 0x4b800000, v104
	v_cmp_gt_f32_e32 vcc, s4, v104
	s_nop 1
	v_cndmask_b32_e32 v104, v104, v105, vcc
	v_rsq_f32_e32 v104, v104
	s_nop 0
	v_mul_f32_e32 v105, 0x45800000, v104
	v_cndmask_b32_e32 v112, v104, v105, vcc
	v_pk_mul_f32 v[40:41], v[40:41], v[112:113] op_sel_hi:[1,0]
	v_pk_mul_f32 v[42:43], v[42:43], v[112:113] op_sel_hi:[1,0]
	v_pk_mul_f32 v[44:45], v[44:45], v[112:113] op_sel_hi:[1,0]
	v_pk_mul_f32 v[46:47], v[46:47], v[112:113] op_sel_hi:[1,0]
	v_pk_mul_f32 v[48:49], v[48:49], v[112:113] op_sel_hi:[1,0]
	v_pk_mul_f32 v[50:51], v[50:51], v[112:113] op_sel_hi:[1,0]
	v_pk_mul_f32 v[52:53], v[52:53], v[112:113] op_sel_hi:[1,0]
	v_pk_mul_f32 v[54:55], v[54:55], v[112:113] op_sel_hi:[1,0]
	s_cmp_lt_u32 s5, 0x4000
	s_cbranch_scc0 .Lxn_w0_l1b
	s_waitcnt vmcnt(4)
	s_branch .Lxn_wd_l1b

.Lxn_wd_l1b:
	s_lshl_b32 s4, s16, 11
	s_add_u32 s12, s52, s4
	s_addc_u32 s13, s53, 0
	v_pk_mul_f32 v[40:41], v[56:57], v[40:41]
	v_pk_mul_f32 v[42:43], v[58:59], v[42:43]
	v_pk_add_f32 v[72:73], v[72:73], 1.0 op_sel_hi:[1,0]
	v_pk_add_f32 v[74:75], v[74:75], 1.0 op_sel_hi:[1,0]
	v_pk_fma_f32 v[40:41], v[72:73], v[40:41], v[88:89]
	v_pk_fma_f32 v[42:43], v[74:75], v[42:43], v[90:91]
	v_cvt_pk_bf16_f32 v114, v40, v41
	v_cvt_pk_bf16_f32 v115, v42, v43
	global_store_dwordx2 v21, v[114:115], s[12:13]
	v_pk_mul_f32 v[44:45], v[60:61], v[44:45]
	v_pk_mul_f32 v[46:47], v[62:63], v[46:47]
	v_pk_add_f32 v[76:77], v[76:77], 1.0 op_sel_hi:[1,0]
	v_pk_add_f32 v[78:79], v[78:79], 1.0 op_sel_hi:[1,0]
	v_pk_fma_f32 v[44:45], v[76:77], v[44:45], v[92:93]
	v_pk_fma_f32 v[46:47], v[78:79], v[46:47], v[94:95]
	v_cvt_pk_bf16_f32 v114, v44, v45
	v_cvt_pk_bf16_f32 v115, v46, v47
	global_store_dwordx2 v21, v[114:115], s[12:13] offset:512
	v_pk_mul_f32 v[48:49], v[64:65], v[48:49]
	v_pk_mul_f32 v[50:51], v[66:67], v[50:51]
	v_pk_add_f32 v[80:81], v[80:81], 1.0 op_sel_hi:[1,0]
	v_pk_add_f32 v[82:83], v[82:83], 1.0 op_sel_hi:[1,0]
	v_pk_fma_f32 v[48:49], v[80:81], v[48:49], v[96:97]
	v_pk_fma_f32 v[50:51], v[82:83], v[50:51], v[98:99]
	v_cvt_pk_bf16_f32 v114, v48, v49
	v_cvt_pk_bf16_f32 v115, v50, v51
	global_store_dwordx2 v21, v[114:115], s[12:13] offset:1024
	v_pk_mul_f32 v[52:53], v[68:69], v[52:53]
	v_pk_mul_f32 v[54:55], v[70:71], v[54:55]
	v_pk_add_f32 v[84:85], v[84:85], 1.0 op_sel_hi:[1,0]
	v_pk_add_f32 v[86:87], v[86:87], 1.0 op_sel_hi:[1,0]
	v_pk_fma_f32 v[52:53], v[84:85], v[52:53], v[100:101]
	v_pk_fma_f32 v[54:55], v[86:87], v[54:55], v[102:103]
	v_cvt_pk_bf16_f32 v114, v52, v53
	v_cvt_pk_bf16_f32 v115, v54, v55
	global_store_dwordx2 v21, v[114:115], s[12:13] offset:1536
	s_mov_b32 s16, s5
	s_cmp_lt_u32 s16, 0x4000
	s_cbranch_scc1 .Lxn_loop_l1
.Lxn_done:
.LBB0_363:
	s_or_b64 exec, exec, s[6:7]
	s_getreg_b32 s4, hwreg(HW_REG_XCC_ID, 0, 4)
	s_waitcnt vmcnt(0)
	s_barrier
	s_and_saveexec_b64 s[0:1], s[94:95]
	s_cbranch_execz .LBB0_415
	s_waitcnt vmcnt(0) expcnt(0) lgkmcnt(0)
	ds_read_b32 v2, v4
	ds_read_b32 v0, v4 offset:4
	s_and_b32 s10, s4, 15
	s_waitcnt lgkmcnt(1)
	v_cmp_ne_u32_e32 vcc, 0, v2
	s_cbranch_vccnz .LBB0_379
	s_mov_b32 s11, 1
	s_branch .LBB0_367

.LBB0_1053:
	ds_bpermute_b32 v0, v146, v148
	s_lshl_b32 s68, s17, 7
	v_lshlrev_b32_e32 v10, 3, v132
	v_mov_b32_e32 v11, v4
	s_waitcnt lgkmcnt(0)
	v_add_f32_e32 v0, v148, v0
	v_div_scale_f32 v1, s[0:1], v0, v0, 1.0
	v_rcp_f32_e32 v2, v1
	s_add_i32 s0, s19, s18
	v_fma_f32 v3, -v1, v2, 1.0
	v_fmac_f32_e32 v2, v3, v2
	v_div_scale_f32 v3, vcc, 1.0, v0, 1.0
	v_mul_f32_e32 v5, v3, v2
	v_fma_f32 v6, -v1, v5, v3
	v_fmac_f32_e32 v5, v6, v2
	v_fma_f32 v1, -v1, v5, v3
	v_div_fmas_f32 v1, v1, v2, v5
	v_add_u32_e32 v2, s0, v133
	v_ashrrev_i32_e32 v3, 31, v2
	v_mov_b64_e32 v[6:7], s[26:27]
	v_mad_i64_i32 v[8:9], s[0:1], v2, s92, v[6:7]
	v_lshlrev_b64 v[2:3], 9, v[2:3]
	v_sub_co_u32_e32 v2, vcc, 0, v2
	v_lshl_add_u64 v[6:7], v[8:9], 0, s[68:69]
	s_nop 0
	v_subb_co_u32_e32 v3, vcc, 0, v3, vcc
	v_lshl_add_u64 v[2:3], v[8:9], 0, v[2:3]
	v_lshl_add_u64 v[12:13], v[6:7], 0, v[10:11]
	s_mov_b64 s[0:1], 0x4512600
	v_lshl_add_u64 v[2:3], v[2:3], 0, s[68:69]
	v_lshl_add_u64 v[6:7], v[12:13], 0, s[0:1]
	v_lshl_add_u64 v[8:9], v[2:3], 0, v[10:11]
	s_mov_b64 s[0:1], 0x6d12400
	v_lshl_add_u64 v[2:3], v[8:9], 0, s[0:1]
	v_div_fixup_f32 v0, v1, v0, 1.0
	global_load_dwordx2 v[150:151], v[6:7], off
	global_load_dwordx2 v[152:153], v[6:7], off offset:16
	global_load_dwordx2 v[154:155], v[6:7], off offset:32
	global_load_dwordx2 v[156:157], v[6:7], off offset:48
	global_load_dwordx2 v[158:159], v[6:7], off offset:64
	global_load_dwordx2 v[160:161], v[6:7], off offset:80
	global_load_dwordx2 v[162:163], v[6:7], off offset:96
	global_load_dwordx2 v[164:165], v[6:7], off offset:112
	s_waitcnt vmcnt(7)
	v_pk_mul_f32 v[12:13], v[32:33], v[0:1] op_sel_hi:[1,0]
	v_lshlrev_b32_e32 v14, 16, v150
	v_and_b32_e32 v15, 0xffff0000, v150
	v_pk_mul_f32 v[12:13], v[12:13], v[14:15]
	v_pk_mul_f32 v[8:9], v[34:35], v[0:1] op_sel_hi:[1,0]
	v_cvt_pk_bf16_f32 v10, v12, v13
	v_lshlrev_b32_e32 v14, 16, v151
	v_and_b32_e32 v15, 0xffff0000, v151
	v_pk_mul_f32 v[8:9], v[8:9], v[14:15]
	s_nop 0
	v_cvt_pk_bf16_f32 v11, v8, v9
	global_store_dwordx2 v[2:3], v[10:11], off
	s_waitcnt vmcnt(7)
	v_pk_mul_f32 v[12:13], v[36:37], v[0:1] op_sel_hi:[1,0]
	v_lshlrev_b32_e32 v14, 16, v152
	v_and_b32_e32 v15, 0xffff0000, v152
	v_pk_mul_f32 v[12:13], v[12:13], v[14:15]
	v_pk_mul_f32 v[8:9], v[38:39], v[0:1] op_sel_hi:[1,0]
	v_cvt_pk_bf16_f32 v10, v12, v13
	v_lshlrev_b32_e32 v14, 16, v153
	v_and_b32_e32 v15, 0xffff0000, v153
	v_pk_mul_f32 v[8:9], v[8:9], v[14:15]
	s_nop 0
	v_cvt_pk_bf16_f32 v11, v8, v9
	global_store_dwordx2 v[2:3], v[10:11], off offset:16
	s_waitcnt vmcnt(7)
	v_pk_mul_f32 v[12:13], v[40:41], v[0:1] op_sel_hi:[1,0]
	v_lshlrev_b32_e32 v14, 16, v154
	v_and_b32_e32 v15, 0xffff0000, v154
	v_pk_mul_f32 v[12:13], v[12:13], v[14:15]
	v_pk_mul_f32 v[8:9], v[42:43], v[0:1] op_sel_hi:[1,0]
	v_cvt_pk_bf16_f32 v10, v12, v13
	v_lshlrev_b32_e32 v14, 16, v155
	v_and_b32_e32 v15, 0xffff0000, v155
	v_pk_mul_f32 v[8:9], v[8:9], v[14:15]
	s_nop 0
	v_cvt_pk_bf16_f32 v11, v8, v9
	global_store_dwordx2 v[2:3], v[10:11], off offset:32
	s_waitcnt vmcnt(7)
	v_pk_mul_f32 v[12:13], v[44:45], v[0:1] op_sel_hi:[1,0]
	v_lshlrev_b32_e32 v14, 16, v156
	v_and_b32_e32 v15, 0xffff0000, v156
	v_pk_mul_f32 v[12:13], v[12:13], v[14:15]
	v_pk_mul_f32 v[8:9], v[46:47], v[0:1] op_sel_hi:[1,0]
	v_cvt_pk_bf16_f32 v10, v12, v13
	v_lshlrev_b32_e32 v14, 16, v157
	v_and_b32_e32 v15, 0xffff0000, v157
	v_pk_mul_f32 v[8:9], v[8:9], v[14:15]
	s_nop 0
	v_cvt_pk_bf16_f32 v11, v8, v9
	global_store_dwordx2 v[2:3], v[10:11], off offset:48
	s_waitcnt vmcnt(7)
	v_pk_mul_f32 v[12:13], v[16:17], v[0:1] op_sel_hi:[1,0]
	v_lshlrev_b32_e32 v14, 16, v158
	v_and_b32_e32 v15, 0xffff0000, v158
	v_pk_mul_f32 v[12:13], v[12:13], v[14:15]
	v_pk_mul_f32 v[8:9], v[18:19], v[0:1] op_sel_hi:[1,0]
	v_cvt_pk_bf16_f32 v10, v12, v13
	v_lshlrev_b32_e32 v14, 16, v159
	v_and_b32_e32 v15, 0xffff0000, v159
	v_pk_mul_f32 v[8:9], v[8:9], v[14:15]
	s_nop 0
	v_cvt_pk_bf16_f32 v11, v8, v9
	global_store_dwordx2 v[2:3], v[10:11], off offset:64
	s_waitcnt vmcnt(7)
	v_pk_mul_f32 v[12:13], v[20:21], v[0:1] op_sel_hi:[1,0]
	v_lshlrev_b32_e32 v14, 16, v160
	v_and_b32_e32 v15, 0xffff0000, v160
	v_pk_mul_f32 v[12:13], v[12:13], v[14:15]
	v_pk_mul_f32 v[8:9], v[22:23], v[0:1] op_sel_hi:[1,0]
	v_cvt_pk_bf16_f32 v10, v12, v13
	v_lshlrev_b32_e32 v14, 16, v161
	v_and_b32_e32 v15, 0xffff0000, v161
	v_pk_mul_f32 v[8:9], v[8:9], v[14:15]
	s_nop 0
	v_cvt_pk_bf16_f32 v11, v8, v9
	global_store_dwordx2 v[2:3], v[10:11], off offset:80
	s_waitcnt vmcnt(7)
	v_pk_mul_f32 v[12:13], v[24:25], v[0:1] op_sel_hi:[1,0]
	v_lshlrev_b32_e32 v14, 16, v162
	v_and_b32_e32 v15, 0xffff0000, v162
	v_pk_mul_f32 v[12:13], v[12:13], v[14:15]
	v_pk_mul_f32 v[8:9], v[26:27], v[0:1] op_sel_hi:[1,0]
	v_cvt_pk_bf16_f32 v10, v12, v13
	v_lshlrev_b32_e32 v14, 16, v163
	v_and_b32_e32 v15, 0xffff0000, v163
	v_pk_mul_f32 v[8:9], v[8:9], v[14:15]
	s_nop 0
	v_cvt_pk_bf16_f32 v11, v8, v9
	global_store_dwordx2 v[2:3], v[10:11], off offset:96
	s_waitcnt vmcnt(7)
	v_pk_mul_f32 v[12:13], v[28:29], v[0:1] op_sel_hi:[1,0]
	v_lshlrev_b32_e32 v14, 16, v164
	v_and_b32_e32 v15, 0xffff0000, v164
	v_pk_mul_f32 v[12:13], v[12:13], v[14:15]
	v_pk_mul_f32 v[8:9], v[30:31], v[0:1] op_sel_hi:[1,0]
	v_cvt_pk_bf16_f32 v10, v12, v13
	v_lshlrev_b32_e32 v14, 16, v165
	v_and_b32_e32 v15, 0xffff0000, v165
	v_pk_mul_f32 v[8:9], v[8:9], v[14:15]
	s_nop 0
	v_cvt_pk_bf16_f32 v11, v8, v9
	global_store_dwordx2 v[2:3], v[10:11], off offset:112

.LBB0_1511:
	v_add_u32_e32 v235, s57, v5
	v_lshlrev_b32_e32 v234, 5, v139
	v_lshl_add_u32 v232, v235, 12, v234
	v_lshlrev_b32_e32 v233, 4, v139
	v_lshl_add_u32 v233, v235, 11, v233
	s_lshl_b32 s16, s10, 8
	s_or_b32 s16, s16, s91
	s_sub_u32 s0, s11, 32
	s_lshr_b32 s0, s0, 4
	s_add_u32 s0, s0, 1
	s_mul_i32 s0, s0, 0x3000
	s_cmp_lt_u32 s11, 32
	s_cselect_b32 s0, 0, s0
	s_add_u32 s0, s0, 0x2000
	s_lshl_b32 s1, s16, 2
	s_add_u32 s0, s0, s1
	s_add_u32 s6, s66, s0
	s_addc_u32 s7, s67, 0
	global_load_dwordx4 v[182:185], v234, s[6:7]
	global_load_dwordx4 v[186:189], v234, s[6:7] offset:16
	global_load_dwordx4 v[190:193], v234, s[6:7] offset:512
	global_load_dwordx4 v[194:197], v234, s[6:7] offset:528
	s_lshl_b32 s0, s11, 19
	s_lshl_b32 s1, s16, 1
	s_add_u32 s0, s0, s1
	s_add_u32 s14, s72, s0
	s_addc_u32 s15, s73, 0
	s_and_b64 vcc, exec, s[62:63]
	s_cbranch_vccnz .Lwout_l1
.Lwout_l0:
	s_cmp_lt_u32 s11, 32
	s_cselect_b32 s12, s36, s38
	s_cselect_b32 s13, s37, s39
	s_and_b32 s0, s11, 31
	s_lshl_b32 s0, s0, 20
	s_add_u32 s12, s12, s0
	s_addc_u32 s13, s13, 0
	s_lshl_b32 s0, s16, 2
	s_add_u32 s12, s12, s0
	s_addc_u32 s13, s13, 0
	s_add_u32 s0, s12, 0x0
	s_addc_u32 s1, s13, 0
	global_load_dwordx4 v[130:133], v232, s[0:1]
	global_load_dwordx4 v[134:137], v232, s[0:1] offset:16
	s_add_u32 s0, s12, 0x10000
	s_addc_u32 s1, s13, 0
	global_load_dwordx4 v[156:159], v232, s[0:1]
	global_load_dwordx4 v[160:163], v232, s[0:1] offset:16
	s_add_u32 s0, s12, 0x20000
	s_addc_u32 s1, s13, 0
	global_load_dwordx4 v[164:167], v232, s[0:1]
	global_load_dwordx4 v[168:171], v232, s[0:1] offset:16
	s_add_u32 s0, s12, 0x30000
	s_addc_u32 s1, s13, 0
	global_load_dwordx4 v[172:175], v232, s[0:1]
	global_load_dwordx4 v[176:179], v232, s[0:1] offset:16
	s_add_u32 s0, s12, 0x80000
	s_addc_u32 s1, s13, 0
	global_load_dwordx4 v[198:201], v232, s[0:1]
	global_load_dwordx4 v[202:205], v232, s[0:1] offset:16
	s_add_u32 s0, s12, 0x90000
	s_addc_u32 s1, s13, 0
	global_load_dwordx4 v[206:209], v232, s[0:1]
	global_load_dwordx4 v[210:213], v232, s[0:1] offset:16
	s_waitcnt vmcnt(10)
	v_pk_fma_f32 v[126:127], v[126:127], v[182:183], v[130:131]
	v_pk_fma_f32 v[128:129], v[128:129], v[184:185], v[132:133]
	v_pk_fma_f32 v[122:123], v[122:123], v[186:187], v[134:135]
	v_pk_fma_f32 v[124:125], v[124:125], v[188:189], v[136:137]
	v_cvt_pk_bf16_f32 v126, v126, v127
	v_cvt_pk_bf16_f32 v127, v128, v129
	v_cvt_pk_bf16_f32 v128, v122, v123
	v_cvt_pk_bf16_f32 v129, v124, v125
	s_add_u32 s8, s14, 0x0
	s_addc_u32 s9, s15, 0
	global_store_dwordx4 v233, v[126:129], s[8:9]
	s_add_u32 s0, s12, 0xa0000
	s_addc_u32 s1, s13, 0
	global_load_dwordx4 v[130:133], v232, s[0:1]
	global_load_dwordx4 v[134:137], v232, s[0:1] offset:16
	s_waitcnt vmcnt(11)
	v_pk_fma_f32 v[118:119], v[118:119], v[182:183], v[156:157]
	v_pk_fma_f32 v[120:121], v[120:121], v[184:185], v[158:159]
	v_pk_fma_f32 v[114:115], v[114:115], v[186:187], v[160:161]
	v_pk_fma_f32 v[116:117], v[116:117], v[188:189], v[162:163]
	v_cvt_pk_bf16_f32 v118, v118, v119
	v_cvt_pk_bf16_f32 v119, v120, v121
	v_cvt_pk_bf16_f32 v120, v114, v115
	v_cvt_pk_bf16_f32 v121, v116, v117
	s_add_u32 s8, s14, 0x8000
	s_addc_u32 s9, s15, 0
	global_store_dwordx4 v233, v[118:121], s[8:9]
	s_add_u32 s0, s12, 0xb0000
	s_addc_u32 s1, s13, 0
	global_load_dwordx4 v[156:159], v232, s[0:1]
	global_load_dwordx4 v[160:163], v232, s[0:1] offset:16
	s_waitcnt vmcnt(12)
	v_pk_fma_f32 v[110:111], v[110:111], v[182:183], v[164:165]
	v_pk_fma_f32 v[112:113], v[112:113], v[184:185], v[166:167]
	v_pk_fma_f32 v[106:107], v[106:107], v[186:187], v[168:169]
	v_pk_fma_f32 v[108:109], v[108:109], v[188:189], v[170:171]
	v_cvt_pk_bf16_f32 v110, v110, v111
	v_cvt_pk_bf16_f32 v111, v112, v113
	v_cvt_pk_bf16_f32 v112, v106, v107
	v_cvt_pk_bf16_f32 v113, v108, v109
	s_add_u32 s8, s14, 0x10000
	s_addc_u32 s9, s15, 0
	global_store_dwordx4 v233, v[110:113], s[8:9]
	s_add_u32 s0, s12, 0x200
	s_addc_u32 s1, s13, 0
	global_load_dwordx4 v[164:167], v232, s[0:1]
	global_load_dwordx4 v[168:171], v232, s[0:1] offset:16
	s_waitcnt vmcnt(13)
	v_pk_fma_f32 v[102:103], v[102:103], v[182:183], v[172:173]
	v_pk_fma_f32 v[104:105], v[104:105], v[184:185], v[174:175]
	v_pk_fma_f32 v[98:99], v[98:99], v[186:187], v[176:177]
	v_pk_fma_f32 v[100:101], v[100:101], v[188:189], v[178:179]
	v_cvt_pk_bf16_f32 v102, v102, v103
	v_cvt_pk_bf16_f32 v103, v104, v105
	v_cvt_pk_bf16_f32 v104, v98, v99
	v_cvt_pk_bf16_f32 v105, v100, v101
	s_add_u32 s8, s14, 0x18000
	s_addc_u32 s9, s15, 0
	global_store_dwordx4 v233, v[102:105], s[8:9]
	s_add_u32 s0, s12, 0x10200
	s_addc_u32 s1, s13, 0
	global_load_dwordx4 v[172:175], v232, s[0:1]
	global_load_dwordx4 v[176:179], v232, s[0:1] offset:16
	s_waitcnt vmcnt(14)
	v_pk_fma_f32 v[94:95], v[94:95], v[182:183], v[198:199]
	v_pk_fma_f32 v[96:97], v[96:97], v[184:185], v[200:201]
	v_pk_fma_f32 v[90:91], v[90:91], v[186:187], v[202:203]
	v_pk_fma_f32 v[92:93], v[92:93], v[188:189], v[204:205]
	v_cvt_pk_bf16_f32 v94, v94, v95
	v_cvt_pk_bf16_f32 v95, v96, v97
	v_cvt_pk_bf16_f32 v96, v90, v91
	v_cvt_pk_bf16_f32 v97, v92, v93
	s_add_u32 s8, s14, 0x40000
	s_addc_u32 s9, s15, 0
	global_store_dwordx4 v233, v[94:97], s[8:9]
	s_add_u32 s0, s12, 0x20200
	s_addc_u32 s1, s13, 0
	global_load_dwordx4 v[198:201], v232, s[0:1]
	global_load_dwordx4 v[202:205], v232, s[0:1] offset:16
	s_waitcnt vmcnt(15)
	v_pk_fma_f32 v[86:87], v[86:87], v[182:183], v[206:207]
	v_pk_fma_f32 v[88:89], v[88:89], v[184:185], v[208:209]
	v_pk_fma_f32 v[82:83], v[82:83], v[186:187], v[210:211]
	v_pk_fma_f32 v[84:85], v[84:85], v[188:189], v[212:213]
	v_cvt_pk_bf16_f32 v86, v86, v87
	v_cvt_pk_bf16_f32 v87, v88, v89
	v_cvt_pk_bf16_f32 v88, v82, v83
	v_cvt_pk_bf16_f32 v89, v84, v85
	s_add_u32 s8, s14, 0x48000
	s_addc_u32 s9, s15, 0
	global_store_dwordx4 v233, v[86:89], s[8:9]
	s_add_u32 s0, s12, 0x30200
	s_addc_u32 s1, s13, 0
	global_load_dwordx4 v[206:209], v232, s[0:1]
	global_load_dwordx4 v[210:213], v232, s[0:1] offset:16
	s_waitcnt vmcnt(15)
	v_pk_fma_f32 v[78:79], v[78:79], v[182:183], v[130:131]
	v_pk_fma_f32 v[80:81], v[80:81], v[184:185], v[132:133]
	v_pk_fma_f32 v[74:75], v[74:75], v[186:187], v[134:135]
	v_pk_fma_f32 v[76:77], v[76:77], v[188:189], v[136:137]
	v_cvt_pk_bf16_f32 v78, v78, v79
	v_cvt_pk_bf16_f32 v79, v80, v81
	v_cvt_pk_bf16_f32 v80, v74, v75
	v_cvt_pk_bf16_f32 v81, v76, v77
	s_add_u32 s8, s14, 0x50000
	s_addc_u32 s9, s15, 0
	global_store_dwordx4 v233, v[78:81], s[8:9]
	s_add_u32 s0, s12, 0x80200
	s_addc_u32 s1, s13, 0
	global_load_dwordx4 v[130:133], v232, s[0:1]
	global_load_dwordx4 v[134:137], v232, s[0:1] offset:16
	s_waitcnt vmcnt(15)
	v_pk_fma_f32 v[70:71], v[70:71], v[182:183], v[156:157]
	v_pk_fma_f32 v[72:73], v[72:73], v[184:185], v[158:159]
	v_pk_fma_f32 v[66:67], v[66:67], v[186:187], v[160:161]
	v_pk_fma_f32 v[68:69], v[68:69], v[188:189], v[162:163]
	v_cvt_pk_bf16_f32 v70, v70, v71
	v_cvt_pk_bf16_f32 v71, v72, v73
	v_cvt_pk_bf16_f32 v72, v66, v67
	v_cvt_pk_bf16_f32 v73, v68, v69
	s_add_u32 s8, s14, 0x58000
	s_addc_u32 s9, s15, 0
	global_store_dwordx4 v233, v[70:73], s[8:9]
	s_add_u32 s0, s12, 0x90200
	s_addc_u32 s1, s13, 0
	global_load_dwordx4 v[156:159], v232, s[0:1]
	global_load_dwordx4 v[160:163], v232, s[0:1] offset:16
	s_waitcnt vmcnt(15)
	v_pk_fma_f32 v[62:63], v[62:63], v[190:191], v[164:165]
	v_pk_fma_f32 v[64:65], v[64:65], v[192:193], v[166:167]
	v_pk_fma_f32 v[58:59], v[58:59], v[194:195], v[168:169]
	v_pk_fma_f32 v[60:61], v[60:61], v[196:197], v[170:171]
	v_cvt_pk_bf16_f32 v62, v62, v63
	v_cvt_pk_bf16_f32 v63, v64, v65
	v_cvt_pk_bf16_f32 v64, v58, v59
	v_cvt_pk_bf16_f32 v65, v60, v61
	s_add_u32 s8, s14, 0x100
	s_addc_u32 s9, s15, 0
	global_store_dwordx4 v233, v[62:65], s[8:9]
	s_add_u32 s0, s12, 0xa0200
	s_addc_u32 s1, s13, 0
	global_load_dwordx4 v[164:167], v232, s[0:1]
	global_load_dwordx4 v[168:171], v232, s[0:1] offset:16
	s_waitcnt vmcnt(15)
	v_pk_fma_f32 v[54:55], v[54:55], v[190:191], v[172:173]
	v_pk_fma_f32 v[56:57], v[56:57], v[192:193], v[174:175]
	v_pk_fma_f32 v[50:51], v[50:51], v[194:195], v[176:177]
	v_pk_fma_f32 v[52:53], v[52:53], v[196:197], v[178:179]
	v_cvt_pk_bf16_f32 v54, v54, v55
	v_cvt_pk_bf16_f32 v55, v56, v57
	v_cvt_pk_bf16_f32 v56, v50, v51
	v_cvt_pk_bf16_f32 v57, v52, v53
	s_add_u32 s8, s14, 0x8100
	s_addc_u32 s9, s15, 0
	global_store_dwordx4 v233, v[54:57], s[8:9]
	s_add_u32 s0, s12, 0xb0200
	s_addc_u32 s1, s13, 0
	global_load_dwordx4 v[172:175], v232, s[0:1]
	global_load_dwordx4 v[176:179], v232, s[0:1] offset:16
	s_waitcnt vmcnt(15)
	v_pk_fma_f32 v[46:47], v[46:47], v[190:191], v[198:199]
	v_pk_fma_f32 v[48:49], v[48:49], v[192:193], v[200:201]
	v_pk_fma_f32 v[42:43], v[42:43], v[194:195], v[202:203]
	v_pk_fma_f32 v[44:45], v[44:45], v[196:197], v[204:205]
	v_cvt_pk_bf16_f32 v46, v46, v47
	v_cvt_pk_bf16_f32 v47, v48, v49
	v_cvt_pk_bf16_f32 v48, v42, v43
	v_cvt_pk_bf16_f32 v49, v44, v45
	s_add_u32 s8, s14, 0x10100
	s_addc_u32 s9, s15, 0
	global_store_dwordx4 v233, v[46:49], s[8:9]
	s_waitcnt vmcnt(13)
	v_pk_fma_f32 v[38:39], v[38:39], v[190:191], v[206:207]
	v_pk_fma_f32 v[40:41], v[40:41], v[192:193], v[208:209]
	v_pk_fma_f32 v[34:35], v[34:35], v[194:195], v[210:211]
	v_pk_fma_f32 v[36:37], v[36:37], v[196:197], v[212:213]
	v_cvt_pk_bf16_f32 v38, v38, v39
	v_cvt_pk_bf16_f32 v39, v40, v41
	v_cvt_pk_bf16_f32 v40, v34, v35
	v_cvt_pk_bf16_f32 v41, v36, v37
	s_add_u32 s8, s14, 0x18100
	s_addc_u32 s9, s15, 0
	global_store_dwordx4 v233, v[38:41], s[8:9]
	s_waitcnt vmcnt(11)
	v_pk_fma_f32 v[30:31], v[30:31], v[190:191], v[130:131]
	v_pk_fma_f32 v[32:33], v[32:33], v[192:193], v[132:133]
	v_pk_fma_f32 v[26:27], v[26:27], v[194:195], v[134:135]
	v_pk_fma_f32 v[28:29], v[28:29], v[196:197], v[136:137]
	v_cvt_pk_bf16_f32 v30, v30, v31
	v_cvt_pk_bf16_f32 v31, v32, v33
	v_cvt_pk_bf16_f32 v32, v26, v27
	v_cvt_pk_bf16_f32 v33, v28, v29
	s_add_u32 s8, s14, 0x40100
	s_addc_u32 s9, s15, 0
	global_store_dwordx4 v233, v[30:33], s[8:9]
	s_waitcnt vmcnt(9)
	v_pk_fma_f32 v[22:23], v[22:23], v[190:191], v[156:157]
	v_pk_fma_f32 v[24:25], v[24:25], v[192:193], v[158:159]
	v_pk_fma_f32 v[18:19], v[18:19], v[194:195], v[160:161]
	v_pk_fma_f32 v[20:21], v[20:21], v[196:197], v[162:163]
	v_cvt_pk_bf16_f32 v22, v22, v23
	v_cvt_pk_bf16_f32 v23, v24, v25
	v_cvt_pk_bf16_f32 v24, v18, v19
	v_cvt_pk_bf16_f32 v25, v20, v21
	s_add_u32 s8, s14, 0x48100
	s_addc_u32 s9, s15, 0
	global_store_dwordx4 v233, v[22:25], s[8:9]
	s_waitcnt vmcnt(7)
	v_pk_fma_f32 v[14:15], v[14:15], v[190:191], v[164:165]
	v_pk_fma_f32 v[16:17], v[16:17], v[192:193], v[166:167]
	v_pk_fma_f32 v[10:11], v[10:11], v[194:195], v[168:169]
	v_pk_fma_f32 v[12:13], v[12:13], v[196:197], v[170:171]
	v_cvt_pk_bf16_f32 v14, v14, v15
	v_cvt_pk_bf16_f32 v15, v16, v17
	v_cvt_pk_bf16_f32 v16, v10, v11
	v_cvt_pk_bf16_f32 v17, v12, v13
	s_add_u32 s8, s14, 0x50100
	s_addc_u32 s9, s15, 0
	global_store_dwordx4 v233, v[14:17], s[8:9]
	s_waitcnt vmcnt(5)
	v_pk_fma_f32 v[6:7], v[6:7], v[190:191], v[172:173]
	v_pk_fma_f32 v[8:9], v[8:9], v[192:193], v[174:175]
	v_pk_fma_f32 v[0:1], v[0:1], v[194:195], v[176:177]
	v_pk_fma_f32 v[2:3], v[2:3], v[196:197], v[178:179]
	v_cvt_pk_bf16_f32 v6, v6, v7
	v_cvt_pk_bf16_f32 v7, v8, v9
	v_cvt_pk_bf16_f32 v8, v0, v1
	v_cvt_pk_bf16_f32 v9, v2, v3
	s_add_u32 s8, s14, 0x58100
	s_addc_u32 s9, s15, 0
	global_store_dwordx4 v233, v[6:9], s[8:9]
	s_branch .Lwout_done
.Lwout_l1:
	s_lshl_b32 s0, s11, 19
	s_lshl_b32 s1, s16, 1
	s_add_u32 s0, s0, s1
	s_add_u32 s12, s30, s0
	s_addc_u32 s13, s31, 0
	s_add_u32 s0, s12, 0x0
	s_addc_u32 s1, s13, 0
	global_load_dwordx4 v[130:133], v233, s[0:1]
	s_add_u32 s0, s12, 0x8000
	s_addc_u32 s1, s13, 0
	global_load_dwordx4 v[134:137], v233, s[0:1]
	s_add_u32 s0, s12, 0x10000
	s_addc_u32 s1, s13, 0
	global_load_dwordx4 v[156:159], v233, s[0:1]
	s_add_u32 s0, s12, 0x18000
	s_addc_u32 s1, s13, 0
	global_load_dwordx4 v[160:163], v233, s[0:1]
	s_add_u32 s0, s12, 0x40000
	s_addc_u32 s1, s13, 0
	global_load_dwordx4 v[164:167], v233, s[0:1]
	s_add_u32 s0, s12, 0x48000
	s_addc_u32 s1, s13, 0
	global_load_dwordx4 v[168:171], v233, s[0:1]
	s_add_u32 s0, s12, 0x50000
	s_addc_u32 s1, s13, 0
	global_load_dwordx4 v[172:175], v233, s[0:1]
	s_add_u32 s0, s12, 0x58000
	s_addc_u32 s1, s13, 0
	global_load_dwordx4 v[176:179], v233, s[0:1]
	s_waitcnt vmcnt(7)
	v_lshlrev_b32_e32 v224, 16, v130
	v_and_b32_e32 v225, 0xffff0000, v130
	v_pk_fma_f32 v[126:127], v[126:127], v[182:183], v[224:225]
	v_lshlrev_b32_e32 v226, 16, v131
	v_and_b32_e32 v227, 0xffff0000, v131
	v_pk_fma_f32 v[128:129], v[128:129], v[184:185], v[226:227]
	v_lshlrev_b32_e32 v228, 16, v132
	v_and_b32_e32 v229, 0xffff0000, v132
	v_pk_fma_f32 v[122:123], v[122:123], v[186:187], v[228:229]
	v_lshlrev_b32_e32 v230, 16, v133
	v_and_b32_e32 v231, 0xffff0000, v133
	v_pk_fma_f32 v[124:125], v[124:125], v[188:189], v[230:231]
	v_cvt_pk_bf16_f32 v126, v126, v127
	v_cvt_pk_bf16_f32 v127, v128, v129
	v_cvt_pk_bf16_f32 v128, v122, v123
	v_cvt_pk_bf16_f32 v129, v124, v125
	s_add_u32 s8, s14, 0x0
	s_addc_u32 s9, s15, 0
	global_store_dwordx4 v233, v[126:129], s[8:9]
	s_add_u32 s0, s12, 0x100
	s_addc_u32 s1, s13, 0
	global_load_dwordx4 v[130:133], v233, s[0:1]
	s_waitcnt vmcnt(8)
	v_lshlrev_b32_e32 v224, 16, v134
	v_and_b32_e32 v225, 0xffff0000, v134
	v_pk_fma_f32 v[118:119], v[118:119], v[182:183], v[224:225]
	v_lshlrev_b32_e32 v226, 16, v135
	v_and_b32_e32 v227, 0xffff0000, v135
	v_pk_fma_f32 v[120:121], v[120:121], v[184:185], v[226:227]
	v_lshlrev_b32_e32 v228, 16, v136
	v_and_b32_e32 v229, 0xffff0000, v136
	v_pk_fma_f32 v[114:115], v[114:115], v[186:187], v[228:229]
	v_lshlrev_b32_e32 v230, 16, v137
	v_and_b32_e32 v231, 0xffff0000, v137
	v_pk_fma_f32 v[116:117], v[116:117], v[188:189], v[230:231]
	v_cvt_pk_bf16_f32 v118, v118, v119
	v_cvt_pk_bf16_f32 v119, v120, v121
	v_cvt_pk_bf16_f32 v120, v114, v115
	v_cvt_pk_bf16_f32 v121, v116, v117
	s_add_u32 s8, s14, 0x8000
	s_addc_u32 s9, s15, 0
	global_store_dwordx4 v233, v[118:121], s[8:9]
	s_add_u32 s0, s12, 0x8100
	s_addc_u32 s1, s13, 0
	global_load_dwordx4 v[134:137], v233, s[0:1]
	s_waitcnt vmcnt(9)
	v_lshlrev_b32_e32 v224, 16, v156
	v_and_b32_e32 v225, 0xffff0000, v156
	v_pk_fma_f32 v[110:111], v[110:111], v[182:183], v[224:225]
	v_lshlrev_b32_e32 v226, 16, v157
	v_and_b32_e32 v227, 0xffff0000, v157
	v_pk_fma_f32 v[112:113], v[112:113], v[184:185], v[226:227]
	v_lshlrev_b32_e32 v228, 16, v158
	v_and_b32_e32 v229, 0xffff0000, v158
	v_pk_fma_f32 v[106:107], v[106:107], v[186:187], v[228:229]
	v_lshlrev_b32_e32 v230, 16, v159
	v_and_b32_e32 v231, 0xffff0000, v159
	v_pk_fma_f32 v[108:109], v[108:109], v[188:189], v[230:231]
	v_cvt_pk_bf16_f32 v110, v110, v111
	v_cvt_pk_bf16_f32 v111, v112, v113
	v_cvt_pk_bf16_f32 v112, v106, v107
	v_cvt_pk_bf16_f32 v113, v108, v109
	s_add_u32 s8, s14, 0x10000
	s_addc_u32 s9, s15, 0
	global_store_dwordx4 v233, v[110:113], s[8:9]
	s_add_u32 s0, s12, 0x10100
	s_addc_u32 s1, s13, 0
	global_load_dwordx4 v[156:159], v233, s[0:1]
	s_waitcnt vmcnt(10)
	v_lshlrev_b32_e32 v224, 16, v160
	v_and_b32_e32 v225, 0xffff0000, v160
	v_pk_fma_f32 v[102:103], v[102:103], v[182:183], v[224:225]
	v_lshlrev_b32_e32 v226, 16, v161
	v_and_b32_e32 v227, 0xffff0000, v161
	v_pk_fma_f32 v[104:105], v[104:105], v[184:185], v[226:227]
	v_lshlrev_b32_e32 v228, 16, v162
	v_and_b32_e32 v229, 0xffff0000, v162
	v_pk_fma_f32 v[98:99], v[98:99], v[186:187], v[228:229]
	v_lshlrev_b32_e32 v230, 16, v163
	v_and_b32_e32 v231, 0xffff0000, v163
	v_pk_fma_f32 v[100:101], v[100:101], v[188:189], v[230:231]
	v_cvt_pk_bf16_f32 v102, v102, v103
	v_cvt_pk_bf16_f32 v103, v104, v105
	v_cvt_pk_bf16_f32 v104, v98, v99
	v_cvt_pk_bf16_f32 v105, v100, v101
	s_add_u32 s8, s14, 0x18000
	s_addc_u32 s9, s15, 0
	global_store_dwordx4 v233, v[102:105], s[8:9]
	s_add_u32 s0, s12, 0x18100
	s_addc_u32 s1, s13, 0
	global_load_dwordx4 v[160:163], v233, s[0:1]
	s_waitcnt vmcnt(11)
	v_lshlrev_b32_e32 v224, 16, v164
	v_and_b32_e32 v225, 0xffff0000, v164
	v_pk_fma_f32 v[94:95], v[94:95], v[182:183], v[224:225]
	v_lshlrev_b32_e32 v226, 16, v165
	v_and_b32_e32 v227, 0xffff0000, v165
	v_pk_fma_f32 v[96:97], v[96:97], v[184:185], v[226:227]
	v_lshlrev_b32_e32 v228, 16, v166
	v_and_b32_e32 v229, 0xffff0000, v166
	v_pk_fma_f32 v[90:91], v[90:91], v[186:187], v[228:229]
	v_lshlrev_b32_e32 v230, 16, v167
	v_and_b32_e32 v231, 0xffff0000, v167
	v_pk_fma_f32 v[92:93], v[92:93], v[188:189], v[230:231]
	v_cvt_pk_bf16_f32 v94, v94, v95
	v_cvt_pk_bf16_f32 v95, v96, v97
	v_cvt_pk_bf16_f32 v96, v90, v91
	v_cvt_pk_bf16_f32 v97, v92, v93
	s_add_u32 s8, s14, 0x40000
	s_addc_u32 s9, s15, 0
	global_store_dwordx4 v233, v[94:97], s[8:9]
	s_add_u32 s0, s12, 0x40100
	s_addc_u32 s1, s13, 0
	global_load_dwordx4 v[164:167], v233, s[0:1]
	s_waitcnt vmcnt(12)
	v_lshlrev_b32_e32 v224, 16, v168
	v_and_b32_e32 v225, 0xffff0000, v168
	v_pk_fma_f32 v[86:87], v[86:87], v[182:183], v[224:225]
	v_lshlrev_b32_e32 v226, 16, v169
	v_and_b32_e32 v227, 0xffff0000, v169
	v_pk_fma_f32 v[88:89], v[88:89], v[184:185], v[226:227]
	v_lshlrev_b32_e32 v228, 16, v170
	v_and_b32_e32 v229, 0xffff0000, v170
	v_pk_fma_f32 v[82:83], v[82:83], v[186:187], v[228:229]
	v_lshlrev_b32_e32 v230, 16, v171
	v_and_b32_e32 v231, 0xffff0000, v171
	v_pk_fma_f32 v[84:85], v[84:85], v[188:189], v[230:231]
	v_cvt_pk_bf16_f32 v86, v86, v87
	v_cvt_pk_bf16_f32 v87, v88, v89
	v_cvt_pk_bf16_f32 v88, v82, v83
	v_cvt_pk_bf16_f32 v89, v84, v85
	s_add_u32 s8, s14, 0x48000
	s_addc_u32 s9, s15, 0
	global_store_dwordx4 v233, v[86:89], s[8:9]
	s_add_u32 s0, s12, 0x48100
	s_addc_u32 s1, s13, 0
	global_load_dwordx4 v[168:171], v233, s[0:1]
	s_waitcnt vmcnt(13)
	v_lshlrev_b32_e32 v224, 16, v172
	v_and_b32_e32 v225, 0xffff0000, v172
	v_pk_fma_f32 v[78:79], v[78:79], v[182:183], v[224:225]
	v_lshlrev_b32_e32 v226, 16, v173
	v_and_b32_e32 v227, 0xffff0000, v173
	v_pk_fma_f32 v[80:81], v[80:81], v[184:185], v[226:227]
	v_lshlrev_b32_e32 v228, 16, v174
	v_and_b32_e32 v229, 0xffff0000, v174
	v_pk_fma_f32 v[74:75], v[74:75], v[186:187], v[228:229]
	v_lshlrev_b32_e32 v230, 16, v175
	v_and_b32_e32 v231, 0xffff0000, v175
	v_pk_fma_f32 v[76:77], v[76:77], v[188:189], v[230:231]
	v_cvt_pk_bf16_f32 v78, v78, v79
	v_cvt_pk_bf16_f32 v79, v80, v81
	v_cvt_pk_bf16_f32 v80, v74, v75
	v_cvt_pk_bf16_f32 v81, v76, v77
	s_add_u32 s8, s14, 0x50000
	s_addc_u32 s9, s15, 0
	global_store_dwordx4 v233, v[78:81], s[8:9]
	s_add_u32 s0, s12, 0x50100
	s_addc_u32 s1, s13, 0
	global_load_dwordx4 v[172:175], v233, s[0:1]
	s_waitcnt vmcnt(14)
	v_lshlrev_b32_e32 v224, 16, v176
	v_and_b32_e32 v225, 0xffff0000, v176
	v_pk_fma_f32 v[70:71], v[70:71], v[182:183], v[224:225]
	v_lshlrev_b32_e32 v226, 16, v177
	v_and_b32_e32 v227, 0xffff0000, v177
	v_pk_fma_f32 v[72:73], v[72:73], v[184:185], v[226:227]
	v_lshlrev_b32_e32 v228, 16, v178
	v_and_b32_e32 v229, 0xffff0000, v178
	v_pk_fma_f32 v[66:67], v[66:67], v[186:187], v[228:229]
	v_lshlrev_b32_e32 v230, 16, v179
	v_and_b32_e32 v231, 0xffff0000, v179
	v_pk_fma_f32 v[68:69], v[68:69], v[188:189], v[230:231]
	v_cvt_pk_bf16_f32 v70, v70, v71
	v_cvt_pk_bf16_f32 v71, v72, v73
	v_cvt_pk_bf16_f32 v72, v66, v67
	v_cvt_pk_bf16_f32 v73, v68, v69
	s_add_u32 s8, s14, 0x58000
	s_addc_u32 s9, s15, 0
	global_store_dwordx4 v233, v[70:73], s[8:9]
	s_add_u32 s0, s12, 0x58100
	s_addc_u32 s1, s13, 0
	global_load_dwordx4 v[176:179], v233, s[0:1]
	s_waitcnt vmcnt(14)
	v_lshlrev_b32_e32 v224, 16, v130
	v_and_b32_e32 v225, 0xffff0000, v130
	v_pk_fma_f32 v[62:63], v[62:63], v[190:191], v[224:225]
	v_lshlrev_b32_e32 v226, 16, v131
	v_and_b32_e32 v227, 0xffff0000, v131
	v_pk_fma_f32 v[64:65], v[64:65], v[192:193], v[226:227]
	v_lshlrev_b32_e32 v228, 16, v132
	v_and_b32_e32 v229, 0xffff0000, v132
	v_pk_fma_f32 v[58:59], v[58:59], v[194:195], v[228:229]
	v_lshlrev_b32_e32 v230, 16, v133
	v_and_b32_e32 v231, 0xffff0000, v133
	v_pk_fma_f32 v[60:61], v[60:61], v[196:197], v[230:231]
	v_cvt_pk_bf16_f32 v62, v62, v63
	v_cvt_pk_bf16_f32 v63, v64, v65
	v_cvt_pk_bf16_f32 v64, v58, v59
	v_cvt_pk_bf16_f32 v65, v60, v61
	s_add_u32 s8, s14, 0x100
	s_addc_u32 s9, s15, 0
	global_store_dwordx4 v233, v[62:65], s[8:9]
	s_waitcnt vmcnt(13)
	v_lshlrev_b32_e32 v224, 16, v134
	v_and_b32_e32 v225, 0xffff0000, v134
	v_pk_fma_f32 v[54:55], v[54:55], v[190:191], v[224:225]
	v_lshlrev_b32_e32 v226, 16, v135
	v_and_b32_e32 v227, 0xffff0000, v135
	v_pk_fma_f32 v[56:57], v[56:57], v[192:193], v[226:227]
	v_lshlrev_b32_e32 v228, 16, v136
	v_and_b32_e32 v229, 0xffff0000, v136
	v_pk_fma_f32 v[50:51], v[50:51], v[194:195], v[228:229]
	v_lshlrev_b32_e32 v230, 16, v137
	v_and_b32_e32 v231, 0xffff0000, v137
	v_pk_fma_f32 v[52:53], v[52:53], v[196:197], v[230:231]
	v_cvt_pk_bf16_f32 v54, v54, v55
	v_cvt_pk_bf16_f32 v55, v56, v57
	v_cvt_pk_bf16_f32 v56, v50, v51
	v_cvt_pk_bf16_f32 v57, v52, v53
	s_add_u32 s8, s14, 0x8100
	s_addc_u32 s9, s15, 0
	global_store_dwordx4 v233, v[54:57], s[8:9]
	s_waitcnt vmcnt(12)
	v_lshlrev_b32_e32 v224, 16, v156
	v_and_b32_e32 v225, 0xffff0000, v156
	v_pk_fma_f32 v[46:47], v[46:47], v[190:191], v[224:225]
	v_lshlrev_b32_e32 v226, 16, v157
	v_and_b32_e32 v227, 0xffff0000, v157
	v_pk_fma_f32 v[48:49], v[48:49], v[192:193], v[226:227]
	v_lshlrev_b32_e32 v228, 16, v158
	v_and_b32_e32 v229, 0xffff0000, v158
	v_pk_fma_f32 v[42:43], v[42:43], v[194:195], v[228:229]
	v_lshlrev_b32_e32 v230, 16, v159
	v_and_b32_e32 v231, 0xffff0000, v159
	v_pk_fma_f32 v[44:45], v[44:45], v[196:197], v[230:231]
	v_cvt_pk_bf16_f32 v46, v46, v47
	v_cvt_pk_bf16_f32 v47, v48, v49
	v_cvt_pk_bf16_f32 v48, v42, v43
	v_cvt_pk_bf16_f32 v49, v44, v45
	s_add_u32 s8, s14, 0x10100
	s_addc_u32 s9, s15, 0
	global_store_dwordx4 v233, v[46:49], s[8:9]
	s_waitcnt vmcnt(11)
	v_lshlrev_b32_e32 v224, 16, v160
	v_and_b32_e32 v225, 0xffff0000, v160
	v_pk_fma_f32 v[38:39], v[38:39], v[190:191], v[224:225]
	v_lshlrev_b32_e32 v226, 16, v161
	v_and_b32_e32 v227, 0xffff0000, v161
	v_pk_fma_f32 v[40:41], v[40:41], v[192:193], v[226:227]
	v_lshlrev_b32_e32 v228, 16, v162
	v_and_b32_e32 v229, 0xffff0000, v162
	v_pk_fma_f32 v[34:35], v[34:35], v[194:195], v[228:229]
	v_lshlrev_b32_e32 v230, 16, v163
	v_and_b32_e32 v231, 0xffff0000, v163
	v_pk_fma_f32 v[36:37], v[36:37], v[196:197], v[230:231]
	v_cvt_pk_bf16_f32 v38, v38, v39
	v_cvt_pk_bf16_f32 v39, v40, v41
	v_cvt_pk_bf16_f32 v40, v34, v35
	v_cvt_pk_bf16_f32 v41, v36, v37
	s_add_u32 s8, s14, 0x18100
	s_addc_u32 s9, s15, 0
	global_store_dwordx4 v233, v[38:41], s[8:9]
	s_waitcnt vmcnt(10)
	v_lshlrev_b32_e32 v224, 16, v164
	v_and_b32_e32 v225, 0xffff0000, v164
	v_pk_fma_f32 v[30:31], v[30:31], v[190:191], v[224:225]
	v_lshlrev_b32_e32 v226, 16, v165
	v_and_b32_e32 v227, 0xffff0000, v165
	v_pk_fma_f32 v[32:33], v[32:33], v[192:193], v[226:227]
	v_lshlrev_b32_e32 v228, 16, v166
	v_and_b32_e32 v229, 0xffff0000, v166
	v_pk_fma_f32 v[26:27], v[26:27], v[194:195], v[228:229]
	v_lshlrev_b32_e32 v230, 16, v167
	v_and_b32_e32 v231, 0xffff0000, v167
	v_pk_fma_f32 v[28:29], v[28:29], v[196:197], v[230:231]
	v_cvt_pk_bf16_f32 v30, v30, v31
	v_cvt_pk_bf16_f32 v31, v32, v33
	v_cvt_pk_bf16_f32 v32, v26, v27
	v_cvt_pk_bf16_f32 v33, v28, v29
	s_add_u32 s8, s14, 0x40100
	s_addc_u32 s9, s15, 0
	global_store_dwordx4 v233, v[30:33], s[8:9]
	s_waitcnt vmcnt(9)
	v_lshlrev_b32_e32 v224, 16, v168
	v_and_b32_e32 v225, 0xffff0000, v168
	v_pk_fma_f32 v[22:23], v[22:23], v[190:191], v[224:225]
	v_lshlrev_b32_e32 v226, 16, v169
	v_and_b32_e32 v227, 0xffff0000, v169
	v_pk_fma_f32 v[24:25], v[24:25], v[192:193], v[226:227]
	v_lshlrev_b32_e32 v228, 16, v170
	v_and_b32_e32 v229, 0xffff0000, v170
	v_pk_fma_f32 v[18:19], v[18:19], v[194:195], v[228:229]
	v_lshlrev_b32_e32 v230, 16, v171
	v_and_b32_e32 v231, 0xffff0000, v171
	v_pk_fma_f32 v[20:21], v[20:21], v[196:197], v[230:231]
	v_cvt_pk_bf16_f32 v22, v22, v23
	v_cvt_pk_bf16_f32 v23, v24, v25
	v_cvt_pk_bf16_f32 v24, v18, v19
	v_cvt_pk_bf16_f32 v25, v20, v21
	s_add_u32 s8, s14, 0x48100
	s_addc_u32 s9, s15, 0
	global_store_dwordx4 v233, v[22:25], s[8:9]
	s_waitcnt vmcnt(8)
	v_lshlrev_b32_e32 v224, 16, v172
	v_and_b32_e32 v225, 0xffff0000, v172
	v_pk_fma_f32 v[14:15], v[14:15], v[190:191], v[224:225]
	v_lshlrev_b32_e32 v226, 16, v173
	v_and_b32_e32 v227, 0xffff0000, v173
	v_pk_fma_f32 v[16:17], v[16:17], v[192:193], v[226:227]
	v_lshlrev_b32_e32 v228, 16, v174
	v_and_b32_e32 v229, 0xffff0000, v174
	v_pk_fma_f32 v[10:11], v[10:11], v[194:195], v[228:229]
	v_lshlrev_b32_e32 v230, 16, v175
	v_and_b32_e32 v231, 0xffff0000, v175
	v_pk_fma_f32 v[12:13], v[12:13], v[196:197], v[230:231]
	v_cvt_pk_bf16_f32 v14, v14, v15
	v_cvt_pk_bf16_f32 v15, v16, v17
	v_cvt_pk_bf16_f32 v16, v10, v11
	v_cvt_pk_bf16_f32 v17, v12, v13
	s_add_u32 s8, s14, 0x50100
	s_addc_u32 s9, s15, 0
	global_store_dwordx4 v233, v[14:17], s[8:9]
	s_waitcnt vmcnt(7)
	v_lshlrev_b32_e32 v224, 16, v176
	v_and_b32_e32 v225, 0xffff0000, v176
	v_pk_fma_f32 v[6:7], v[6:7], v[190:191], v[224:225]
	v_lshlrev_b32_e32 v226, 16, v177
	v_and_b32_e32 v227, 0xffff0000, v177
	v_pk_fma_f32 v[8:9], v[8:9], v[192:193], v[226:227]
	v_lshlrev_b32_e32 v228, 16, v178
	v_and_b32_e32 v229, 0xffff0000, v178
	v_pk_fma_f32 v[0:1], v[0:1], v[194:195], v[228:229]
	v_lshlrev_b32_e32 v230, 16, v179
	v_and_b32_e32 v231, 0xffff0000, v179
	v_pk_fma_f32 v[2:3], v[2:3], v[196:197], v[230:231]
	v_cvt_pk_bf16_f32 v6, v6, v7
	v_cvt_pk_bf16_f32 v7, v8, v9
	v_cvt_pk_bf16_f32 v8, v0, v1
	v_cvt_pk_bf16_f32 v9, v2, v3
	s_add_u32 s8, s14, 0x58100
	s_addc_u32 s9, s15, 0
	global_store_dwordx4 v233, v[6:9], s[8:9]
.Lwout_done:
	s_andn2_b64 vcc, exec, s[4:5]
	s_mov_b64 s[0:1], -1
	s_cbranch_vccnz .LBB0_1499
	s_andn2_b64 vcc, exec, s[70:71]
	s_cbranch_vccnz .LBB0_1498
	s_barrier
	s_branch .LBB0_1498
